# attention: V fragment reads 7 deep (private register ring), decision chain behind first PV MFMAs, K reads before DMA; P0a loads in flight; cg sync removed (ring order fixed: no LDS return may race a V
# baseline (speedup 1.0000x reference)
;     ...
;     f32x16 pA0, pA1, pB0, pB1; float alA, alB; bf16x8 pa0, pa1, pa2, pa3;
;     int sp = 0, sc_ = 1, sn = 2;
.LBB0_695:
	s_lshl_b32 s43, s34, 13
	s_mov_b32 s42, s38
	v_lshl_add_u32 v185, s42, 13, v184
	ds_read_b128 v[112:115], v185 offset:49152
	ds_read_b128 v[186:189], v185 offset:49664
	s_add_i32 s38, s43, s39
	s_mov_b32 m0, s38
	v_lshl_add_u64 v[212:213], s[68:69], 0, v[166:167]
	global_load_lds_dwordx4 v[172:173], off
	s_lshl_b32 s38, s34, 14
	s_add_i32 s45, s38, s24
	s_mov_b32 m0, s45
	v_lshl_add_u64 v[214:215], s[68:69], 0, v[170:171]
	global_load_lds_dwordx4 v[212:213], off
	s_add_i32 s38, s38, s25
	s_mov_b32 m0, s38
	s_mov_b32 s38, s44
	global_load_lds_dwordx4 v[214:215], off
	s_waitcnt lgkmcnt(1)
	v_mfma_f32_32x32x16_bf16 v[128:143], v[112:115], v[156:159], v[64:79]
	ds_read_b128 v[190:193], v185 offset:51200
	ds_read_b128 v[194:197], v185 offset:51712
	v_add_f32_e32 v116, 0, v96
	v_add_f32_e32 v117, 0, v97
	v_add_f32_e32 v116, v98, v116
	v_add_f32_e32 v117, v99, v117
	v_cvt_pk_bf16_f32 v96, v96, v97
	v_cvt_pk_bf16_f32 v97, v98, v99
	v_cvt_pk_bf16_f32 v98, v100, v101
	v_cvt_pk_bf16_f32 v99, v102, v103
	s_nop 0
	v_add_f32_e32 v100, v100, v116
	v_add_f32_e32 v101, v101, v117
	s_waitcnt lgkmcnt(2)
	v_mfma_f32_32x32x16_bf16 v[112:127], v[186:189], v[156:159], v[64:79]
	v_add_f32_e32 v100, v102, v100
	v_add_f32_e32 v101, v103, v101
	v_permlane32_swap_b32_e32 v96, v98
	v_permlane32_swap_b32_e32 v97, v99
	s_waitcnt lgkmcnt(1)
	v_mfma_f32_32x32x16_bf16 v[128:143], v[190:193], v[152:155], v[128:143]
	ds_read_b128 v[186:189], v185 offset:53248
	ds_read_b128 v[198:201], v185 offset:53760
	v_add_f32_e32 v100, v104, v100
	v_add_f32_e32 v101, v105, v101
	v_add_f32_e32 v202, v106, v100
	v_add_f32_e32 v203, v107, v101
	v_cvt_pk_bf16_f32 v100, v104, v105
	v_cvt_pk_bf16_f32 v101, v106, v107
	v_cvt_pk_bf16_f32 v102, v108, v109
	v_cvt_pk_bf16_f32 v103, v110, v111
	s_waitcnt lgkmcnt(2)
	v_mfma_f32_32x32x16_bf16 v[112:127], v[194:197], v[152:155], v[112:127]
	v_add_f32_e32 v104, v108, v202
	v_add_f32_e32 v105, v109, v203
	v_add_f32_e32 v190, v110, v104
	v_add_f32_e32 v191, v111, v105
	v_permlane32_swap_b32_e32 v100, v102
	v_permlane32_swap_b32_e32 v101, v103
	s_waitcnt lgkmcnt(1)
	v_mfma_f32_32x32x16_bf16 v[128:143], v[186:189], v[148:151], v[128:143]
	ds_read_b128 v[104:107], v185 offset:55296
	ds_read_b128 v[108:111], v185 offset:55808
	v_add_f32_e32 v185, v80, v190
	v_add_f32_e32 v190, v81, v191
	v_add_f32_e32 v185, v82, v185
	v_add_f32_e32 v190, v83, v190
	v_cvt_pk_bf16_f32 v80, v80, v81
	v_cvt_pk_bf16_f32 v81, v82, v83
	v_cvt_pk_bf16_f32 v82, v84, v85
	v_cvt_pk_bf16_f32 v83, v86, v87
	s_waitcnt lgkmcnt(2)
	v_mfma_f32_32x32x16_bf16 v[112:127], v[198:201], v[148:151], v[112:127]
	s_lshl_b32 s44, s38, 14
	v_add_u32_e32 v189, s44, v183
	ds_read_b64_tr_b16 v[194:195], v189 offset:0
	ds_read_b64_tr_b16 v[196:197], v189 offset:0x800
	ds_read_b64_tr_b16 v[198:199], v189 offset:0x1000
	ds_read_b64_tr_b16 v[200:201], v189 offset:0x1800
	ds_read_b64_tr_b16 v[212:213], v189 offset:0x2000
	ds_read_b64_tr_b16 v[214:215], v189 offset:0x2800
	v_add_f32_e32 v84, v84, v185
	v_add_f32_e32 v85, v85, v190
	v_add_f32_e32 v84, v86, v84
	v_add_f32_e32 v85, v87, v85
	v_permlane32_swap_b32_e32 v80, v82
	v_permlane32_swap_b32_e32 v81, v83
	s_waitcnt lgkmcnt(7)
	v_mfma_f32_32x32x16_bf16 v[128:143], v[104:107], v[144:147], v[128:143]
	ds_read_b64_tr_b16 v[190:191], v189 offset:0x3000
	ds_read_b64_tr_b16 v[192:193], v189 offset:0x3800
	ds_read_b64_tr_b16 v[216:217], v189 offset:0x200
	ds_read_b64_tr_b16 v[218:219], v189 offset:0xa00
	v_add_f32_e32 v84, v88, v84
	v_add_f32_e32 v85, v89, v85
	v_add_f32_e32 v185, v90, v84
	v_add_f32_e32 v186, v91, v85
	v_cvt_pk_bf16_f32 v84, v88, v89
	v_cvt_pk_bf16_f32 v85, v90, v91
	v_cvt_pk_bf16_f32 v86, v92, v93
	v_cvt_pk_bf16_f32 v87, v94, v95
	s_waitcnt lgkmcnt(10)
	v_mfma_f32_32x32x16_bf16 v[112:127], v[108:111], v[144:147], v[112:127]
	v_add_f32_e32 v88, v92, v185
	v_add_f32_e32 v89, v93, v186
	v_add_f32_e32 v88, v94, v88
	v_add_f32_e32 v89, v95, v89
	v_permlane32_swap_b32_e32 v84, v86
	v_permlane32_swap_b32_e32 v85, v87
	ds_read_b64_tr_b16 v[220:221], v189 offset:0x1200
	ds_read_b64_tr_b16 v[222:223], v189 offset:0x1a00
	ds_read_b64_tr_b16 v[224:225], v189 offset:0x2200
	ds_read_b64_tr_b16 v[226:227], v189 offset:0x2a00
	s_waitcnt lgkmcnt(12)
	v_mfma_f32_32x32x16_bf16 v[48:63], v[96:99], v[194:197], v[48:63]
	v_max_f32_e32 v90, v129, v129
	v_max_f32_e32 v91, v128, v128
	v_max_f32_e32 v90, v91, v90
	v_max3_f32 v91, v131, v132, v133
	v_max3_f32 v90, v90, v130, v134
	v_max3_f32 v91, v91, v136, v137
	ds_read_b64_tr_b16 v[194:195], v189 offset:0x3200
	ds_read_b64_tr_b16 v[196:197], v189 offset:0x3a00
	s_waitcnt lgkmcnt(12)
	v_mfma_f32_32x32x16_bf16 v[48:63], v[100:103], v[198:201], v[48:63]
	v_max3_f32 v90, v90, v135, v138
	v_max3_f32 v91, v91, v140, v141
	v_max3_f32 v90, v90, v139, v142
	v_max3_f32 v90, v90, v143, v91
	v_add_f32_e32 v186, v88, v89
	v_mov_b32_e32 v187, v186
	ds_read_b64_tr_b16 v[198:199], v189 offset:0x400
	ds_read_b64_tr_b16 v[200:201], v189 offset:0xc00
	s_waitcnt lgkmcnt(12)
	v_mfma_f32_32x32x16_bf16 v[48:63], v[80:83], v[212:215], v[48:63]
	v_max3_f32 v88, v112, v113, v114
	v_max3_f32 v89, v115, v116, v117
	v_max3_f32 v88, v88, v118, v119
	v_max3_f32 v89, v89, v120, v121
	v_permlane32_swap_b32_e32 v186, v187
	v_max3_f32 v88, v88, v122, v123
	ds_read_b64_tr_b16 v[212:213], v189 offset:0x1400
	ds_read_b64_tr_b16 v[214:215], v189 offset:0x1c00
	s_waitcnt lgkmcnt(12)
	v_mfma_f32_32x32x16_bf16 v[48:63], v[84:87], v[190:193], v[48:63]
	v_max3_f32 v89, v89, v124, v125
	v_max3_f32 v88, v88, v126, v127
	v_max3_f32 v88, v90, v88, v89
	v_mov_b32_e32 v89, v88
	ds_read_b64_tr_b16 v[190:191], v189 offset:0x2400
	ds_read_b64_tr_b16 v[192:193], v189 offset:0x2c00
	s_waitcnt lgkmcnt(12)
	v_mfma_f32_32x32x16_bf16 v[32:47], v[96:99], v[216:219], v[32:47]
	v_permlane32_swap_b32_e32 v88, v89
	v_max_f32_e32 v89, v89, v89
	v_max_f32_e32 v88, v88, v88
	v_max_f32_e32 v88, v88, v89
	v_cmp_lt_f32_e32 vcc, s47, v88
	v_mov_b32_e32 v188, 1.0
	s_cbranch_vccnz .LBB0_707
.Lattn_m0_res1:
	ds_read_b64_tr_b16 v[216:217], v189 offset:0x3400
	ds_read_b64_tr_b16 v[218:219], v189 offset:0x3c00
	s_waitcnt lgkmcnt(12)
	v_mfma_f32_32x32x16_bf16 v[32:47], v[100:103], v[220:223], v[32:47]
	v_exp_f32_e32 v128, v128
	v_exp_f32_e32 v129, v129
	v_exp_f32_e32 v130, v130
	ds_read_b64_tr_b16 v[220:221], v189 offset:0x600
	ds_read_b64_tr_b16 v[222:223], v189 offset:0xe00
	s_waitcnt lgkmcnt(12)
	v_mfma_f32_32x32x16_bf16 v[32:47], v[80:83], v[224:227], v[32:47]
	v_exp_f32_e32 v131, v131
	v_exp_f32_e32 v132, v132
	v_exp_f32_e32 v133, v133
	ds_read_b64_tr_b16 v[224:225], v189 offset:0x1600
	ds_read_b64_tr_b16 v[226:227], v189 offset:0x1e00
	s_waitcnt lgkmcnt(12)
	v_mfma_f32_32x32x16_bf16 v[32:47], v[84:87], v[194:197], v[32:47]
	v_exp_f32_e32 v134, v134
	v_exp_f32_e32 v135, v135
	v_exp_f32_e32 v136, v136
	ds_read_b64_tr_b16 v[194:195], v189 offset:0x2600
	ds_read_b64_tr_b16 v[196:197], v189 offset:0x2e00
	s_waitcnt lgkmcnt(12)
	v_mfma_f32_32x32x16_bf16 v[16:31], v[96:99], v[198:201], v[16:31]
	v_exp_f32_e32 v137, v137
	v_exp_f32_e32 v138, v138
	v_exp_f32_e32 v139, v139
	ds_read_b64_tr_b16 v[198:199], v189 offset:0x3600
	ds_read_b64_tr_b16 v[200:201], v189 offset:0x3e00
	s_waitcnt lgkmcnt(12)
	v_mfma_f32_32x32x16_bf16 v[16:31], v[100:103], v[212:215], v[16:31]
	v_exp_f32_e32 v140, v140
	v_exp_f32_e32 v141, v141
	v_exp_f32_e32 v142, v142
	s_waitcnt lgkmcnt(10)
	v_mfma_f32_32x32x16_bf16 v[16:31], v[80:83], v[190:193], v[16:31]
	v_exp_f32_e32 v143, v143
	v_exp_f32_e32 v112, v112
	v_exp_f32_e32 v113, v113
	s_waitcnt lgkmcnt(8)
	v_mfma_f32_32x32x16_bf16 v[16:31], v[84:87], v[216:219], v[16:31]
	v_exp_f32_e32 v114, v114
	v_exp_f32_e32 v115, v115
	v_exp_f32_e32 v116, v116
	s_waitcnt lgkmcnt(6)
	v_mfma_f32_32x32x16_bf16 v[0:15], v[96:99], v[220:223], v[0:15]
	v_exp_f32_e32 v117, v117
	v_exp_f32_e32 v118, v118
	v_exp_f32_e32 v119, v119
	s_waitcnt lgkmcnt(4)
	v_mfma_f32_32x32x16_bf16 v[0:15], v[100:103], v[224:227], v[0:15]
	v_exp_f32_e32 v120, v120
	v_exp_f32_e32 v121, v121
	v_exp_f32_e32 v122, v122
	s_waitcnt lgkmcnt(2)
	v_mfma_f32_32x32x16_bf16 v[0:15], v[80:83], v[194:197], v[0:15]
	v_exp_f32_e32 v123, v123
	v_exp_f32_e32 v124, v124
	v_exp_f32_e32 v125, v125
	s_waitcnt lgkmcnt(0)
	v_mfma_f32_32x32x16_bf16 v[0:15], v[84:87], v[198:201], v[0:15]
	v_exp_f32_e32 v126, v126
	v_exp_f32_e32 v127, v127
	v_cmp_gt_f32_e32 vcc, 1.0, v188
	s_cbranch_vccz .LBB0_700
	s_and_saveexec_b64 s[70:71], s[0:1]
	ds_write_b32 v177, v188 offset:128
	s_or_b64 exec, exec, s[70:71]
	s_waitcnt lgkmcnt(0)
	v_add_u32_e32 v92, s19, v168
	ds_read_b128 v[80:83], v92 offset:224
	ds_read_b128 v[84:87], v92 offset:192
	ds_read_b128 v[88:91], v92 offset:160
	ds_read_b128 v[92:95], v92 offset:128
	s_waitcnt lgkmcnt(3)
	v_pk_mul_f32 v[60:61], v[60:61], v[80:81]
	s_waitcnt lgkmcnt(2)
	v_pk_mul_f32 v[56:57], v[56:57], v[84:85]
	s_waitcnt lgkmcnt(1)
	v_pk_mul_f32 v[52:53], v[52:53], v[88:89]
	v_pk_mul_f32 v[62:63], v[62:63], v[82:83]
	v_pk_mul_f32 v[58:59], v[58:59], v[86:87]
	v_pk_mul_f32 v[54:55], v[54:55], v[90:91]
	s_waitcnt lgkmcnt(0)
	v_pk_mul_f32 v[50:51], v[50:51], v[94:95]
	v_pk_mul_f32 v[48:49], v[48:49], v[92:93]
	v_pk_mul_f32 v[44:45], v[44:45], v[80:81]
	v_pk_mul_f32 v[40:41], v[40:41], v[84:85]
	v_pk_mul_f32 v[36:37], v[36:37], v[88:89]
	v_pk_mul_f32 v[46:47], v[46:47], v[82:83]
	v_pk_mul_f32 v[42:43], v[42:43], v[86:87]
	v_pk_mul_f32 v[38:39], v[38:39], v[90:91]
	v_pk_mul_f32 v[34:35], v[34:35], v[94:95]
	v_pk_mul_f32 v[32:33], v[32:33], v[92:93]
	v_pk_mul_f32 v[28:29], v[28:29], v[80:81]
	v_pk_mul_f32 v[24:25], v[24:25], v[84:85]
	v_pk_mul_f32 v[20:21], v[20:21], v[88:89]
	v_pk_mul_f32 v[30:31], v[30:31], v[82:83]
	v_pk_mul_f32 v[26:27], v[26:27], v[86:87]
	v_pk_mul_f32 v[22:23], v[22:23], v[90:91]
	v_pk_mul_f32 v[18:19], v[18:19], v[94:95]
	v_pk_mul_f32 v[16:17], v[16:17], v[92:93]
	v_pk_mul_f32 v[12:13], v[12:13], v[80:81]
	v_pk_mul_f32 v[8:9], v[8:9], v[84:85]
	v_pk_mul_f32 v[4:5], v[4:5], v[88:89]
	v_pk_mul_f32 v[14:15], v[14:15], v[82:83]
	v_pk_mul_f32 v[10:11], v[10:11], v[86:87]
	v_pk_mul_f32 v[6:7], v[6:7], v[90:91]
	v_pk_mul_f32 v[2:3], v[2:3], v[94:95]
	v_pk_mul_f32 v[0:1], v[0:1], v[92:93]

;     ...
;     f32x16 pA0, pA1, pB0, pB1; float alA, alB; bf16x8 pa0, pa1, pa2, pa3;
;     int sp = 0, sc_ = 1, sn = 2;
.LBB0_720:
	s_lshl_b32 s43, s34, 13
	s_mov_b32 s42, s38
	v_lshl_add_u32 v187, s42, 13, v186
	ds_read_b128 v[112:115], v187 offset:49152
	ds_read_b128 v[188:191], v187 offset:49664
	s_add_i32 s38, s43, s39
	s_mov_b32 m0, s38
	v_lshl_add_u64 v[212:213], s[4:5], 0, v[166:167]
	global_load_lds_dwordx4 v[172:173], off
	s_lshl_b32 s38, s34, 14
	s_add_i32 s45, s38, s24
	s_mov_b32 m0, s45
	v_lshl_add_u64 v[214:215], s[4:5], 0, v[170:171]
	global_load_lds_dwordx4 v[212:213], off
	s_add_i32 s38, s38, s25
	s_mov_b32 m0, s38
	s_mov_b32 s38, s44
	global_load_lds_dwordx4 v[214:215], off
	s_waitcnt lgkmcnt(1)
	v_mfma_f32_32x32x16_bf16 v[128:143], v[112:115], v[156:159], v[64:79]
	ds_read_b128 v[192:195], v187 offset:51200
	ds_read_b128 v[196:199], v187 offset:51712
	v_add_f32_e32 v116, 0, v96
	v_add_f32_e32 v117, 0, v97
	v_add_f32_e32 v116, v98, v116
	v_add_f32_e32 v117, v99, v117
	v_cvt_pk_bf16_f32 v96, v96, v97
	v_cvt_pk_bf16_f32 v97, v98, v99
	v_cvt_pk_bf16_f32 v98, v100, v101
	v_cvt_pk_bf16_f32 v99, v102, v103
	s_nop 0
	v_add_f32_e32 v100, v100, v116
	v_add_f32_e32 v101, v101, v117
	s_waitcnt lgkmcnt(2)
	v_mfma_f32_32x32x16_bf16 v[112:127], v[188:191], v[156:159], v[64:79]
	v_add_f32_e32 v100, v102, v100
	v_add_f32_e32 v101, v103, v101
	v_permlane32_swap_b32_e32 v96, v98
	v_permlane32_swap_b32_e32 v97, v99
	s_waitcnt lgkmcnt(1)
	v_mfma_f32_32x32x16_bf16 v[128:143], v[192:195], v[152:155], v[128:143]
	ds_read_b128 v[188:191], v187 offset:53248
	ds_read_b128 v[200:203], v187 offset:53760
	v_add_f32_e32 v100, v104, v100
	v_add_f32_e32 v101, v105, v101
	v_add_f32_e32 v204, v106, v100
	v_add_f32_e32 v205, v107, v101
	v_cvt_pk_bf16_f32 v100, v104, v105
	v_cvt_pk_bf16_f32 v101, v106, v107
	v_cvt_pk_bf16_f32 v102, v108, v109
	v_cvt_pk_bf16_f32 v103, v110, v111
	s_waitcnt lgkmcnt(2)
	v_mfma_f32_32x32x16_bf16 v[112:127], v[196:199], v[152:155], v[112:127]
	v_add_f32_e32 v104, v108, v204
	v_add_f32_e32 v105, v109, v205
	v_add_f32_e32 v192, v110, v104
	v_add_f32_e32 v193, v111, v105
	v_permlane32_swap_b32_e32 v100, v102
	v_permlane32_swap_b32_e32 v101, v103
	s_waitcnt lgkmcnt(1)
	v_mfma_f32_32x32x16_bf16 v[128:143], v[188:191], v[148:151], v[128:143]
	ds_read_b128 v[104:107], v187 offset:55296
	ds_read_b128 v[108:111], v187 offset:55808
	v_add_f32_e32 v187, v80, v192
	v_add_f32_e32 v192, v81, v193
	v_add_f32_e32 v187, v82, v187
	v_add_f32_e32 v192, v83, v192
	v_cvt_pk_bf16_f32 v80, v80, v81
	v_cvt_pk_bf16_f32 v81, v82, v83
	v_cvt_pk_bf16_f32 v82, v84, v85
	v_cvt_pk_bf16_f32 v83, v86, v87
	s_waitcnt lgkmcnt(2)
	v_mfma_f32_32x32x16_bf16 v[112:127], v[200:203], v[148:151], v[112:127]
	s_lshl_b32 s44, s38, 14
	v_add_u32_e32 v191, s44, v185
	ds_read_b64_tr_b16 v[196:197], v191 offset:0
	ds_read_b64_tr_b16 v[198:199], v191 offset:0x800
	ds_read_b64_tr_b16 v[200:201], v191 offset:0x1000
	ds_read_b64_tr_b16 v[202:203], v191 offset:0x1800
	ds_read_b64_tr_b16 v[212:213], v191 offset:0x2000
	ds_read_b64_tr_b16 v[214:215], v191 offset:0x2800
	v_add_f32_e32 v84, v84, v187
	v_add_f32_e32 v85, v85, v192
	v_add_f32_e32 v84, v86, v84
	v_add_f32_e32 v85, v87, v85
	v_permlane32_swap_b32_e32 v80, v82
	v_permlane32_swap_b32_e32 v81, v83
	s_waitcnt lgkmcnt(7)
	v_mfma_f32_32x32x16_bf16 v[128:143], v[104:107], v[144:147], v[128:143]
	ds_read_b64_tr_b16 v[192:193], v191 offset:0x3000
	ds_read_b64_tr_b16 v[194:195], v191 offset:0x3800
	ds_read_b64_tr_b16 v[216:217], v191 offset:0x200
	ds_read_b64_tr_b16 v[218:219], v191 offset:0xa00
	v_add_f32_e32 v84, v88, v84
	v_add_f32_e32 v85, v89, v85
	v_add_f32_e32 v187, v90, v84
	v_add_f32_e32 v188, v91, v85
	v_cvt_pk_bf16_f32 v84, v88, v89
	v_cvt_pk_bf16_f32 v85, v90, v91
	v_cvt_pk_bf16_f32 v86, v92, v93
	v_cvt_pk_bf16_f32 v87, v94, v95
	s_waitcnt lgkmcnt(10)
	v_mfma_f32_32x32x16_bf16 v[112:127], v[108:111], v[144:147], v[112:127]
	v_add_f32_e32 v88, v92, v187
	v_add_f32_e32 v89, v93, v188
	v_add_f32_e32 v88, v94, v88
	v_add_f32_e32 v89, v95, v89
	v_permlane32_swap_b32_e32 v84, v86
	v_permlane32_swap_b32_e32 v85, v87
	ds_read_b64_tr_b16 v[220:221], v191 offset:0x1200
	ds_read_b64_tr_b16 v[222:223], v191 offset:0x1a00
	ds_read_b64_tr_b16 v[224:225], v191 offset:0x2200
	ds_read_b64_tr_b16 v[226:227], v191 offset:0x2a00
	s_waitcnt lgkmcnt(12)
	v_mfma_f32_32x32x16_bf16 v[48:63], v[96:99], v[196:199], v[48:63]
	v_max_f32_e32 v90, v129, v129
	v_max_f32_e32 v91, v128, v128
	v_max_f32_e32 v90, v91, v90
	v_max3_f32 v91, v131, v132, v133
	v_max3_f32 v90, v90, v130, v134
	v_max3_f32 v91, v91, v136, v137
	ds_read_b64_tr_b16 v[196:197], v191 offset:0x3200
	ds_read_b64_tr_b16 v[198:199], v191 offset:0x3a00
	s_waitcnt lgkmcnt(12)
	v_mfma_f32_32x32x16_bf16 v[48:63], v[100:103], v[200:203], v[48:63]
	v_max3_f32 v90, v90, v135, v138
	v_max3_f32 v91, v91, v140, v141
	v_max3_f32 v90, v90, v139, v142
	v_max3_f32 v90, v90, v143, v91
	v_add_f32_e32 v188, v88, v89
	v_mov_b32_e32 v189, v188
	ds_read_b64_tr_b16 v[200:201], v191 offset:0x400
	ds_read_b64_tr_b16 v[202:203], v191 offset:0xc00
	s_waitcnt lgkmcnt(12)
	v_mfma_f32_32x32x16_bf16 v[48:63], v[80:83], v[212:215], v[48:63]
	v_max3_f32 v88, v112, v113, v114
	v_max3_f32 v89, v115, v116, v117
	v_max3_f32 v88, v88, v118, v119
	v_max3_f32 v89, v89, v120, v121
	v_permlane32_swap_b32_e32 v188, v189
	v_max3_f32 v88, v88, v122, v123
	ds_read_b64_tr_b16 v[212:213], v191 offset:0x1400
	ds_read_b64_tr_b16 v[214:215], v191 offset:0x1c00
	s_waitcnt lgkmcnt(12)
	v_mfma_f32_32x32x16_bf16 v[48:63], v[84:87], v[192:195], v[48:63]
	v_max3_f32 v89, v89, v124, v125
	v_max3_f32 v88, v88, v126, v127
	v_max3_f32 v88, v90, v88, v89
	v_mov_b32_e32 v89, v88
	ds_read_b64_tr_b16 v[192:193], v191 offset:0x2400
	ds_read_b64_tr_b16 v[194:195], v191 offset:0x2c00
	s_waitcnt lgkmcnt(12)
	v_mfma_f32_32x32x16_bf16 v[32:47], v[96:99], v[216:219], v[32:47]
	v_permlane32_swap_b32_e32 v88, v89
	v_max_f32_e32 v89, v89, v89
	v_max_f32_e32 v88, v88, v88
	v_max_f32_e32 v88, v88, v89
	v_cmp_lt_f32_e32 vcc, s47, v88
	v_mov_b32_e32 v190, 1.0
	s_cbranch_vccnz .LBB0_732
.Lattn_m1_res1:
	ds_read_b64_tr_b16 v[216:217], v191 offset:0x3400
	ds_read_b64_tr_b16 v[218:219], v191 offset:0x3c00
	s_waitcnt lgkmcnt(12)
	v_mfma_f32_32x32x16_bf16 v[32:47], v[100:103], v[220:223], v[32:47]
	v_exp_f32_e32 v128, v128
	v_exp_f32_e32 v129, v129
	v_exp_f32_e32 v130, v130
	ds_read_b64_tr_b16 v[220:221], v191 offset:0x600
	ds_read_b64_tr_b16 v[222:223], v191 offset:0xe00
	s_waitcnt lgkmcnt(12)
	v_mfma_f32_32x32x16_bf16 v[32:47], v[80:83], v[224:227], v[32:47]
	v_exp_f32_e32 v131, v131
	v_exp_f32_e32 v132, v132
	v_exp_f32_e32 v133, v133
	ds_read_b64_tr_b16 v[224:225], v191 offset:0x1600
	ds_read_b64_tr_b16 v[226:227], v191 offset:0x1e00
	s_waitcnt lgkmcnt(12)
	v_mfma_f32_32x32x16_bf16 v[32:47], v[84:87], v[196:199], v[32:47]
	v_exp_f32_e32 v134, v134
	v_exp_f32_e32 v135, v135
	v_exp_f32_e32 v136, v136
	ds_read_b64_tr_b16 v[196:197], v191 offset:0x2600
	ds_read_b64_tr_b16 v[198:199], v191 offset:0x2e00
	s_waitcnt lgkmcnt(12)
	v_mfma_f32_32x32x16_bf16 v[16:31], v[96:99], v[200:203], v[16:31]
	v_exp_f32_e32 v137, v137
	v_exp_f32_e32 v138, v138
	v_exp_f32_e32 v139, v139
	ds_read_b64_tr_b16 v[200:201], v191 offset:0x3600
	ds_read_b64_tr_b16 v[202:203], v191 offset:0x3e00
	s_waitcnt lgkmcnt(12)
	v_mfma_f32_32x32x16_bf16 v[16:31], v[100:103], v[212:215], v[16:31]
	v_exp_f32_e32 v140, v140
	v_exp_f32_e32 v141, v141
	v_exp_f32_e32 v142, v142
	s_waitcnt lgkmcnt(10)
	v_mfma_f32_32x32x16_bf16 v[16:31], v[80:83], v[192:195], v[16:31]
	v_exp_f32_e32 v143, v143
	v_exp_f32_e32 v112, v112
	v_exp_f32_e32 v113, v113
	s_waitcnt lgkmcnt(8)
	v_mfma_f32_32x32x16_bf16 v[16:31], v[84:87], v[216:219], v[16:31]
	v_exp_f32_e32 v114, v114
	v_exp_f32_e32 v115, v115
	v_exp_f32_e32 v116, v116
	s_waitcnt lgkmcnt(6)
	v_mfma_f32_32x32x16_bf16 v[0:15], v[96:99], v[220:223], v[0:15]
	v_exp_f32_e32 v117, v117
	v_exp_f32_e32 v118, v118
	v_exp_f32_e32 v119, v119
	s_waitcnt lgkmcnt(4)
	v_mfma_f32_32x32x16_bf16 v[0:15], v[100:103], v[224:227], v[0:15]
	v_exp_f32_e32 v120, v120
	v_exp_f32_e32 v121, v121
	v_exp_f32_e32 v122, v122
	s_waitcnt lgkmcnt(2)
	v_mfma_f32_32x32x16_bf16 v[0:15], v[80:83], v[196:199], v[0:15]
	v_exp_f32_e32 v123, v123
	v_exp_f32_e32 v124, v124
	v_exp_f32_e32 v125, v125
	s_waitcnt lgkmcnt(0)
	v_mfma_f32_32x32x16_bf16 v[0:15], v[84:87], v[200:203], v[0:15]
	v_exp_f32_e32 v126, v126
	v_exp_f32_e32 v127, v127
	v_cmp_gt_f32_e32 vcc, 1.0, v190
	s_cbranch_vccz .LBB0_725
	s_and_saveexec_b64 s[52:53], s[0:1]
	ds_write_b32 v180, v190 offset:128
	s_or_b64 exec, exec, s[52:53]
	s_waitcnt lgkmcnt(0)
	v_add_u32_e32 v92, s19, v168
	ds_read_b128 v[80:83], v92 offset:224
	ds_read_b128 v[84:87], v92 offset:192
	ds_read_b128 v[88:91], v92 offset:160
	ds_read_b128 v[92:95], v92 offset:128
	s_waitcnt lgkmcnt(3)
	v_pk_mul_f32 v[60:61], v[60:61], v[80:81]
	s_waitcnt lgkmcnt(2)
	v_pk_mul_f32 v[56:57], v[56:57], v[84:85]
	s_waitcnt lgkmcnt(1)
	v_pk_mul_f32 v[52:53], v[52:53], v[88:89]
	v_pk_mul_f32 v[62:63], v[62:63], v[82:83]
	v_pk_mul_f32 v[58:59], v[58:59], v[86:87]
	v_pk_mul_f32 v[54:55], v[54:55], v[90:91]
	s_waitcnt lgkmcnt(0)
	v_pk_mul_f32 v[50:51], v[50:51], v[94:95]
	v_pk_mul_f32 v[48:49], v[48:49], v[92:93]
	v_pk_mul_f32 v[44:45], v[44:45], v[80:81]
	v_pk_mul_f32 v[40:41], v[40:41], v[84:85]
	v_pk_mul_f32 v[36:37], v[36:37], v[88:89]
	v_pk_mul_f32 v[46:47], v[46:47], v[82:83]
	v_pk_mul_f32 v[42:43], v[42:43], v[86:87]
	v_pk_mul_f32 v[38:39], v[38:39], v[90:91]
	v_pk_mul_f32 v[34:35], v[34:35], v[94:95]
	v_pk_mul_f32 v[32:33], v[32:33], v[92:93]
	v_pk_mul_f32 v[28:29], v[28:29], v[80:81]
	v_pk_mul_f32 v[24:25], v[24:25], v[84:85]
	v_pk_mul_f32 v[20:21], v[20:21], v[88:89]
	v_pk_mul_f32 v[30:31], v[30:31], v[82:83]
	v_pk_mul_f32 v[26:27], v[26:27], v[86:87]
	v_pk_mul_f32 v[22:23], v[22:23], v[90:91]
	v_pk_mul_f32 v[18:19], v[18:19], v[94:95]
	v_pk_mul_f32 v[16:17], v[16:17], v[92:93]
	v_pk_mul_f32 v[12:13], v[12:13], v[80:81]
	v_pk_mul_f32 v[8:9], v[8:9], v[84:85]
	v_pk_mul_f32 v[4:5], v[4:5], v[88:89]
	v_pk_mul_f32 v[14:15], v[14:15], v[82:83]
	v_pk_mul_f32 v[10:11], v[10:11], v[86:87]
	v_pk_mul_f32 v[6:7], v[6:7], v[90:91]
	v_pk_mul_f32 v[2:3], v[2:3], v[94:95]
	v_pk_mul_f32 v[0:1], v[0:1], v[92:93]
